# PF(0)->PA(1) seam: grid barrier replaced by the panel-group barrier plus a device-wide next-layer-w_in-converted counter (write-through conversion stores)
# speedup vs baseline: 1.0479x; 1.0108x over previous
; #define LAS __attribute__((address_space(3)))
; __global__ void __launch_bounds__(NWAVES * 64, 2) mk_fwd(Args args) {
;     ...
;             pg8::gemm_phase<pg8::EpiProj, pg8::StaticOrder, true, true>(lds + RING_OFF, g, S, E);
;             {
;                 const int rem = ((M / 256) * (INW / 256)) % G;
;                 int lane_o = lane; asm volatile("" : "+v"(lane_o));
;                 if ((int)blockIdx.x >= rem) convert_layer_items(args.in, ws, l, ((int)blockIdx.x - rem) * NWAVES + wave, (G - rem) * NWAVES, (LAS float*)(lds + RING_OFF + wave * TR_SCR_BYTES), lane_o, 1);
.LBB0_170:
	v_readlane_b32 s6, v242, 38
	v_readlane_b32 s7, v242, 39
	s_nop 3
	s_and_saveexec_b64 s[98:99], s[6:7]
	s_cbranch_execz .Lpa_arr_done
	v_readlane_b32 s6, v239, 63
	v_readlane_b32 s7, v241, 0
	v_readlane_b32 s100, v242, 4
	s_nop 3
	s_lshr_b32 s100, s100, 6
	s_lshl_b32 s100, s100, 2
	v_mov_b32_e32 v4, s100
	s_cmp_ge_u32 s101, 5
	s_cselect_b32 s100, 2, 1
	v_mov_b32_e32 v3, s100
	s_nop 1
	global_store_dword v4, v3, s[6:7] offset:160 sc1

; __device__ __forceinline__ unsigned xb_add(unsigned* p, unsigned v) { return __hip_atomic_fetch_add(p, v, __ATOMIC_RELAXED, __HIP_MEMORY_SCOPE_AGENT); }
; #define SEAM(k) do { if (IN(k) && IN((k) + 1)) { xcd_barrier(bar); xcd_barrier(bar); } } while (0)
; #define SEAM(k) do { if (IN(k) && IN((k) + 1)) xcd_barrier(bar); } while (0)
; __device__ __forceinline__ void xcd_barrier(const XcdBarrier& b) {
;     asm volatile("s_waitcnt vmcnt(0)" ::: "memory");
;     __syncthreads();
;     if (threadIdx.x == 0) {
;         unsigned* bar = b.bar;
;         __builtin_amdgcn_s_waitcnt(0);
;         unsigned nloc = b.st[0], nx = b.st[1];
;         if (nloc == 0u) { xcd_barrier_complete(bar, b.x, nloc, nx); b.st[0] = nloc; b.st[1] = nx; }
;         const unsigned old = xb_add(&bar[XB_XSUB(b.x)], 1u);
; __global__ void __launch_bounds__(NWAVES * 64, 2) mk_fwd(Args args) {
;     ...
;         SEAM(pb + 0);
.LBB0_225:
	s_xor_b64 s[6:7], s[50:51], -1
	v_writelane_b32 v238, s6, 51
	s_nop 1
	v_writelane_b32 v238, s7, 52
	s_nop 0
	v_readlane_b32 s6, v238, 44
	s_add_i32 s23, s6, 2
	s_cmp_lt_i32 s23, s5
	s_cselect_b64 s[36:37], -1, 0
	s_and_b64 s[24:25], s[40:41], s[36:37]
	s_andn2_b64 vcc, exec, s[24:25]
	s_cbranch_vccnz .LBB0_279
	s_waitcnt vmcnt(0)
	v_readlane_b32 s6, v242, 38
	v_readlane_b32 s7, v242, 39
	s_waitcnt vmcnt(0) lgkmcnt(0)
	s_barrier
	s_and_saveexec_b64 s[38:39], s[6:7]
	s_cbranch_execz .LBB0_278
	v_readlane_b32 s6, v242, 52
	v_readlane_b32 s7, v242, 53
	s_nop 3
	s_cmp_eq_u64 s[6:7], 0
	s_cbranch_scc0 .Lpa_seam_grid
	v_readlane_b32 s6, v240, 60
	v_readlane_b32 s7, v240, 61
	v_mov_b32_e32 v3, 1
	s_nop 4
	global_atomic_add v66, v3, s[6:7] offset:512
	buffer_inv sc1
	s_cmp_ge_u32 s101, 5
	s_cselect_b32 s100, 2, 1
	v_readlane_b32 s6, v239, 63
	v_readlane_b32 s7, v241, 0
	v_readlane_b32 s98, v242, 4
	s_nop 3
	s_and_b32 s99, s98, 7
	s_lshl_b32 s99, s99, 3
	s_bfe_u32 s98, s98, 0x30003
	s_add_i32 s98, s98, s99
	s_mov_b32 s99, 0

; __device__ __forceinline__ unsigned xb_ld(unsigned* p)              { return __hip_atomic_load(p, __ATOMIC_RELAXED, __HIP_MEMORY_SCOPE_AGENT); }
; __device__ __forceinline__ unsigned xb_add(unsigned* p, unsigned v) { return __hip_atomic_fetch_add(p, v, __ATOMIC_RELAXED, __HIP_MEMORY_SCOPE_AGENT); }
; #define XB_SPIN(cond, bar) do { unsigned _sp = 0; while (cond) { __builtin_amdgcn_s_sleep(1); \
;     if ((++_sp & 255u) == 0u) { if (xb_ld(&(bar)[XB_TMO])) break; if (_sp > XB_SPIN_CAP) { atomicAdd(&(bar)[XB_TMO], 1u); break; } } } } while (0)
; #define SEAM_G(k) do { if (IN(k) && IN((k) + 1)) { if (xl_fast) xcc_local_barrier(ctl + CW_BAR2, bar.x, bar.st[0], bar.bar); else xcd_barrier(bar); } } while (0)
; #define SEAM_G(k) SEAM(k)
; __device__ __forceinline__ void xcc_local_barrier(unsigned* bar2, unsigned x, unsigned nloc, unsigned* tmobar) {
;     asm volatile("s_waitcnt vmcnt(0)" ::: "memory");
;     __syncthreads();
;     if (threadIdx.x == 0) {
;         const unsigned old = xb_add(&bar2[XB_XSUB(x)], 1u);
;         const unsigned gen = old / nloc;
;         if (old + 1u == (gen + 1u) * nloc) (void)xb_add(&bar2[XB_XGEN(x)], 1u);
;         else XB_SPIN(xb_ld(&bar2[XB_XGEN(x)]) == gen, tmobar);
;         __builtin_amdgcn_fence(__ATOMIC_ACQUIRE, "agent");
;         asm volatile("s_waitcnt vmcnt(0)" ::: "memory");
;     }
;     __syncthreads();
; }
; __global__ void __launch_bounds__(NWAVES * 64, 2) mk_fwd(Args args) {
;     ...
;         SEAM_G(pb + 1);
;         if (xl_fast && (int)blockIdx.x < 64 && tid == 0) (void)xb_add(ctl + CW_PBD + 64 * (((int)blockIdx.x % 8) * 8 + ((int)blockIdx.x / 8) % 8), 1u);
.LBB0_478:
	s_and_b64 vcc, exec, s[38:39]
	s_cbranch_vccz .LBB0_498
	v_readlane_b32 s6, v238, 25
	s_nop 1
	v_mov_b32_e32 v2, s6
	ds_read_b32 v2, v2
	s_waitcnt vmcnt(0)
	v_readlane_b32 s6, v242, 38
	v_readlane_b32 s7, v242, 39
	s_waitcnt vmcnt(0) lgkmcnt(0)
	s_barrier
	s_and_saveexec_b64 s[38:39], s[6:7]
	s_cbranch_execz .LBB0_497
	v_readlane_b32 s6, v240, 60
	v_readlane_b32 s7, v240, 61
	s_cmp_ge_u32 s101, 5
	s_cselect_b32 s100, 2, 1
	s_lshl_b32 s100, s100, 8
	s_mov_b32 s99, 0
	s_nop 1

; #define GAS __attribute__((address_space(1)))
; #define LAS __attribute__((address_space(3)))
; __device__ __forceinline__ unsigned pk2(float lo, float hi) { f32x2p v = {lo, hi}; bf16x2p b = __builtin_convertvector(v, bf16x2p); return __builtin_bit_cast(unsigned, b); }
; template <int GU>
; __device__ __forceinline__ void p0_transpose_item(const float* W, int N, const float* kscale, bf16* WT, int ldt, int koff, LAS float* scr, int item, int lane) {
;     ...
;     for (int j = 0; j < 8; ++j) { const int n = (lane >> 3) + 8 * j; const LAS float* s = scr + (8 * c) * TR_PITCH + n;
;         v4u o; o.x = pk2(s[0 * TR_PITCH] * s0.x, s[1 * TR_PITCH] * s0.y); o.y = pk2(s[2 * TR_PITCH] * s0.z, s[3 * TR_PITCH] * s0.w);
;         o.z = pk2(s[4 * TR_PITCH] * s1.x, s[5 * TR_PITCH] * s1.y); o.w = pk2(s[6 * TR_PITCH] * s1.z, s[7 * TR_PITCH] * s1.w);
;         const int ng = n0 + n; int drow;
;         if (GU == 0) drow = ng;
;         else if (GU == 3) { const int gsel = (ng >= 2304) ? 1 : 0, j = ng - 1280 - 1024 * gsel; drow = (ng < 1280) ? ng : (1280 + 256 * (j >> 7) + 128 * gsel + (j & 127)); }
;         else drow = 256 * (ng >> 7) + (GU - 1) * 128 + (ng & 127);
;         *(GAS v4u*)(WT + (size_t)drow * ldt + koff + k0 + 8 * c) = o; }
.LBB0_801:
	s_or_b64 exec, exec, s[42:43]
	s_lshl_b32 s84, s24, 1
	s_waitcnt lgkmcnt(0)
	v_pk_mul_f32 v[12:13], v[4:5], v[12:13]
	v_ashrrev_i32_e32 v21, 31, v20
	v_lshl_add_u64 v[10:11], v[76:77], 0, s[84:85]
	v_pk_mul_f32 v[18:19], v[6:7], v[18:19]
	v_pk_mul_f32 v[16:17], v[8:9], v[16:17]
	v_pk_mul_f32 v[14:15], v[2:3], v[14:15]
	v_cvt_pk_bf16_f32 v27, v12, v13
	v_lshlrev_b64 v[12:13], 11, v[20:21]
	v_cvt_pk_bf16_f32 v24, v18, v19
	v_cvt_pk_bf16_f32 v25, v16, v17
	v_cvt_pk_bf16_f32 v26, v14, v15
	v_lshl_add_u64 v[12:13], v[10:11], 0, v[12:13]
	global_store_dwordx4 v[12:13], v[24:27], off sc1
	ds_read2_b32 v[18:19], v84 offset0:8 offset1:73
	ds_read2_b32 v[16:17], v84 offset0:138 offset1:203
	ds_read2_b32 v[14:15], v23 offset0:12 offset1:77
	ds_read2_b32 v[12:13], v23 offset0:142 offset1:207
	v_add_u32_e32 v20, 8, v22
	s_movk_i32 s6, 0x4ff
	v_cmp_lt_i32_e32 vcc, s6, v20
	s_and_saveexec_b64 s[42:43], vcc
	s_cbranch_execz .LBB0_803
	s_movk_i32 s6, 0x8ff
	v_cmp_lt_u32_e32 vcc, s6, v20
	s_nop 1
	v_cndmask_b32_e32 v21, 0, v198, vcc
	v_add_u32_e32 v21, v20, v21
	v_lshl_add_u32 v21, v21, 1, v199
	v_and_b32_e32 v21, 0xffffff00, v21
	v_cndmask_b32_e32 v24, 0, v200, vcc
	v_and_b32_e32 v20, 0x7f, v20
	v_or3_b32 v20, v21, v24, v20
	v_add_u32_e32 v20, 0x500, v20
.LBB0_803:
	s_or_b64 exec, exec, s[42:43]
	s_waitcnt lgkmcnt(0)
	v_pk_mul_f32 v[12:13], v[4:5], v[12:13]
	v_ashrrev_i32_e32 v21, 31, v20
	v_pk_mul_f32 v[18:19], v[6:7], v[18:19]
	v_pk_mul_f32 v[16:17], v[8:9], v[16:17]
	v_pk_mul_f32 v[14:15], v[2:3], v[14:15]
	v_cvt_pk_bf16_f32 v27, v12, v13
	v_lshlrev_b64 v[12:13], 11, v[20:21]
	v_cvt_pk_bf16_f32 v24, v18, v19
	v_cvt_pk_bf16_f32 v25, v16, v17
	v_cvt_pk_bf16_f32 v26, v14, v15
	v_lshl_add_u64 v[12:13], v[10:11], 0, v[12:13]
	global_store_dwordx4 v[12:13], v[24:27], off sc1
	ds_read2_b32 v[18:19], v84 offset0:16 offset1:81
	ds_read2_b32 v[16:17], v84 offset0:146 offset1:211
	ds_read2_b32 v[14:15], v23 offset0:20 offset1:85
	ds_read2_b32 v[12:13], v23 offset0:150 offset1:215
	v_add_u32_e32 v20, 16, v22
	s_movk_i32 s6, 0x4ff
	v_cmp_lt_i32_e32 vcc, s6, v20
	s_and_saveexec_b64 s[42:43], vcc
	s_cbranch_execz .LBB0_805
	s_movk_i32 s6, 0x8ff
	v_cmp_lt_u32_e32 vcc, s6, v20
	s_nop 1
	v_cndmask_b32_e32 v21, 0, v198, vcc
	v_add_u32_e32 v21, v20, v21
	v_lshl_add_u32 v21, v21, 1, v199
	v_and_b32_e32 v21, 0xffffff00, v21
	v_cndmask_b32_e32 v24, 0, v200, vcc
	v_and_b32_e32 v20, 0x7f, v20
	v_or3_b32 v20, v21, v24, v20
	v_add_u32_e32 v20, 0x500, v20
.LBB0_805:
	s_or_b64 exec, exec, s[42:43]
	s_waitcnt lgkmcnt(0)
	v_pk_mul_f32 v[12:13], v[4:5], v[12:13]
	v_ashrrev_i32_e32 v21, 31, v20
	v_pk_mul_f32 v[18:19], v[6:7], v[18:19]
	v_pk_mul_f32 v[16:17], v[8:9], v[16:17]
	v_pk_mul_f32 v[14:15], v[2:3], v[14:15]
	v_cvt_pk_bf16_f32 v27, v12, v13
	v_lshlrev_b64 v[12:13], 11, v[20:21]
	v_cvt_pk_bf16_f32 v24, v18, v19
	v_cvt_pk_bf16_f32 v25, v16, v17
	v_cvt_pk_bf16_f32 v26, v14, v15
	v_lshl_add_u64 v[12:13], v[10:11], 0, v[12:13]
	global_store_dwordx4 v[12:13], v[24:27], off sc1
	ds_read2_b32 v[18:19], v84 offset0:24 offset1:89
	ds_read2_b32 v[16:17], v84 offset0:154 offset1:219
	ds_read2_b32 v[14:15], v23 offset0:28 offset1:93
	ds_read2_b32 v[12:13], v23 offset0:158 offset1:223
	v_add_u32_e32 v20, 24, v22
	s_movk_i32 s6, 0x4ff
	v_cmp_lt_i32_e32 vcc, s6, v20
	s_and_saveexec_b64 s[42:43], vcc
	s_cbranch_execz .LBB0_807
	s_movk_i32 s6, 0x8ff
	v_cmp_lt_u32_e32 vcc, s6, v20
	s_nop 1
	v_cndmask_b32_e32 v21, 0, v198, vcc
	v_add_u32_e32 v21, v20, v21
	v_lshl_add_u32 v21, v21, 1, v199
	v_and_b32_e32 v21, 0xffffff00, v21
	v_cndmask_b32_e32 v24, 0, v200, vcc
	v_and_b32_e32 v20, 0x7f, v20
	v_or3_b32 v20, v21, v24, v20
	v_add_u32_e32 v20, 0x500, v20
.LBB0_807:
	s_or_b64 exec, exec, s[42:43]
	s_waitcnt lgkmcnt(0)
	v_pk_mul_f32 v[12:13], v[4:5], v[12:13]
	v_ashrrev_i32_e32 v21, 31, v20
	v_pk_mul_f32 v[18:19], v[6:7], v[18:19]
	v_pk_mul_f32 v[16:17], v[8:9], v[16:17]
	v_pk_mul_f32 v[14:15], v[2:3], v[14:15]
	v_cvt_pk_bf16_f32 v27, v12, v13
	v_lshlrev_b64 v[12:13], 11, v[20:21]
	v_cvt_pk_bf16_f32 v24, v18, v19
	v_cvt_pk_bf16_f32 v25, v16, v17
	v_cvt_pk_bf16_f32 v26, v14, v15
	v_lshl_add_u64 v[12:13], v[10:11], 0, v[12:13]
	global_store_dwordx4 v[12:13], v[24:27], off sc1
	ds_read2_b32 v[18:19], v84 offset0:32 offset1:97
	ds_read2_b32 v[16:17], v84 offset0:162 offset1:227
	ds_read2_b32 v[14:15], v23 offset0:36 offset1:101
	ds_read2_b32 v[12:13], v23 offset0:166 offset1:231
	v_add_u32_e32 v20, 32, v22
	s_movk_i32 s6, 0x4ff
	v_cmp_lt_i32_e32 vcc, s6, v20
	s_and_saveexec_b64 s[42:43], vcc
	s_cbranch_execz .LBB0_809
	s_movk_i32 s6, 0x8ff
	v_cmp_lt_u32_e32 vcc, s6, v20
	s_nop 1
	v_cndmask_b32_e32 v21, 0, v198, vcc
	v_add_u32_e32 v21, v20, v21
	v_lshl_add_u32 v21, v21, 1, v199
	v_and_b32_e32 v21, 0xffffff00, v21
	v_cndmask_b32_e32 v24, 0, v200, vcc
	v_and_b32_e32 v20, 0x7f, v20
	v_or3_b32 v20, v21, v24, v20
	v_add_u32_e32 v20, 0x500, v20
; #define GAS __attribute__((address_space(1)))
; #define LAS __attribute__((address_space(3)))
; __device__ __forceinline__ unsigned pk2(float lo, float hi) { f32x2p v = {lo, hi}; bf16x2p b = __builtin_convertvector(v, bf16x2p); return __builtin_bit_cast(unsigned, b); }
; template <int GU>
; __device__ __forceinline__ void p0_transpose_item(const float* W, int N, const float* kscale, bf16* WT, int ldt, int koff, LAS float* scr, int item, int lane) {
;     ...
;     for (int j = 0; j < 8; ++j) { const int n = (lane >> 3) + 8 * j; const LAS float* s = scr + (8 * c) * TR_PITCH + n;
;         v4u o; o.x = pk2(s[0 * TR_PITCH] * s0.x, s[1 * TR_PITCH] * s0.y); o.y = pk2(s[2 * TR_PITCH] * s0.z, s[3 * TR_PITCH] * s0.w);
;         o.z = pk2(s[4 * TR_PITCH] * s1.x, s[5 * TR_PITCH] * s1.y); o.w = pk2(s[6 * TR_PITCH] * s1.z, s[7 * TR_PITCH] * s1.w);
;         const int ng = n0 + n; int drow;
;         if (GU == 0) drow = ng;
;         else if (GU == 3) { const int gsel = (ng >= 2304) ? 1 : 0, j = ng - 1280 - 1024 * gsel; drow = (ng < 1280) ? ng : (1280 + 256 * (j >> 7) + 128 * gsel + (j & 127)); }
;         else drow = 256 * (ng >> 7) + (GU - 1) * 128 + (ng & 127);
;         *(GAS v4u*)(WT + (size_t)drow * ldt + koff + k0 + 8 * c) = o; }
.LBB0_809:
	s_or_b64 exec, exec, s[42:43]
	s_waitcnt lgkmcnt(0)
	v_pk_mul_f32 v[12:13], v[4:5], v[12:13]
	v_ashrrev_i32_e32 v21, 31, v20
	v_pk_mul_f32 v[18:19], v[6:7], v[18:19]
	v_pk_mul_f32 v[16:17], v[8:9], v[16:17]
	v_pk_mul_f32 v[14:15], v[2:3], v[14:15]
	v_cvt_pk_bf16_f32 v27, v12, v13
	v_lshlrev_b64 v[12:13], 11, v[20:21]
	v_cvt_pk_bf16_f32 v24, v18, v19
	v_cvt_pk_bf16_f32 v25, v16, v17
	v_cvt_pk_bf16_f32 v26, v14, v15
	v_lshl_add_u64 v[12:13], v[10:11], 0, v[12:13]
	global_store_dwordx4 v[12:13], v[24:27], off sc1
	ds_read2_b32 v[18:19], v84 offset0:40 offset1:105
	ds_read2_b32 v[16:17], v84 offset0:170 offset1:235
	ds_read2_b32 v[14:15], v23 offset0:44 offset1:109
	ds_read2_b32 v[12:13], v23 offset0:174 offset1:239
	v_add_u32_e32 v20, 40, v22
	s_movk_i32 s6, 0x4ff
	v_cmp_lt_i32_e32 vcc, s6, v20
	s_and_saveexec_b64 s[42:43], vcc
	s_cbranch_execz .LBB0_811
	s_movk_i32 s6, 0x8ff
	v_cmp_lt_u32_e32 vcc, s6, v20
	s_nop 1
	v_cndmask_b32_e32 v21, 0, v198, vcc
	v_add_u32_e32 v21, v20, v21
	v_lshl_add_u32 v21, v21, 1, v199
	v_and_b32_e32 v21, 0xffffff00, v21
	v_cndmask_b32_e32 v24, 0, v200, vcc
	v_and_b32_e32 v20, 0x7f, v20
	v_or3_b32 v20, v21, v24, v20
	v_add_u32_e32 v20, 0x500, v20
.LBB0_811:
	s_or_b64 exec, exec, s[42:43]
	s_waitcnt lgkmcnt(0)
	v_pk_mul_f32 v[12:13], v[4:5], v[12:13]
	v_ashrrev_i32_e32 v21, 31, v20
	v_pk_mul_f32 v[18:19], v[6:7], v[18:19]
	v_pk_mul_f32 v[16:17], v[8:9], v[16:17]
	v_pk_mul_f32 v[14:15], v[2:3], v[14:15]
	v_cvt_pk_bf16_f32 v27, v12, v13
	v_lshlrev_b64 v[12:13], 11, v[20:21]
	v_cvt_pk_bf16_f32 v24, v18, v19
	v_cvt_pk_bf16_f32 v25, v16, v17
	v_cvt_pk_bf16_f32 v26, v14, v15
	v_lshl_add_u64 v[12:13], v[10:11], 0, v[12:13]
	global_store_dwordx4 v[12:13], v[24:27], off sc1
	ds_read2_b32 v[18:19], v84 offset0:48 offset1:113
	ds_read2_b32 v[16:17], v84 offset0:178 offset1:243
	ds_read2_b32 v[14:15], v23 offset0:52 offset1:117
	ds_read2_b32 v[12:13], v23 offset0:182 offset1:247
	v_add_u32_e32 v20, 48, v22
	s_movk_i32 s6, 0x4ff
	v_cmp_lt_i32_e32 vcc, s6, v20
	s_and_saveexec_b64 s[42:43], vcc
	s_cbranch_execz .LBB0_813
	s_movk_i32 s6, 0x8ff
	v_cmp_lt_u32_e32 vcc, s6, v20
	s_nop 1
	v_cndmask_b32_e32 v21, 0, v198, vcc
	v_add_u32_e32 v21, v20, v21
	v_lshl_add_u32 v21, v21, 1, v199
	v_and_b32_e32 v21, 0xffffff00, v21
	v_cndmask_b32_e32 v24, 0, v200, vcc
	v_and_b32_e32 v20, 0x7f, v20
	v_or3_b32 v20, v21, v24, v20
	v_add_u32_e32 v20, 0x500, v20
.LBB0_813:
	s_or_b64 exec, exec, s[42:43]
	s_waitcnt lgkmcnt(0)
	v_pk_mul_f32 v[12:13], v[4:5], v[12:13]
	v_ashrrev_i32_e32 v21, 31, v20
	v_pk_mul_f32 v[18:19], v[6:7], v[18:19]
	v_pk_mul_f32 v[16:17], v[8:9], v[16:17]
	v_pk_mul_f32 v[14:15], v[2:3], v[14:15]
	v_cvt_pk_bf16_f32 v27, v12, v13
	v_lshlrev_b64 v[12:13], 11, v[20:21]
	v_cvt_pk_bf16_f32 v24, v18, v19
	v_cvt_pk_bf16_f32 v25, v16, v17
	v_cvt_pk_bf16_f32 v26, v14, v15
	v_lshl_add_u64 v[12:13], v[10:11], 0, v[12:13]
	global_store_dwordx4 v[12:13], v[24:27], off sc1
	ds_read2_b32 v[18:19], v84 offset0:56 offset1:121
	ds_read2_b32 v[16:17], v84 offset0:186 offset1:251
	ds_read2_b32 v[14:15], v23 offset0:60 offset1:125
	ds_read2_b32 v[12:13], v23 offset0:190 offset1:255
	v_add_u32_e32 v20, 56, v22
	s_movk_i32 s6, 0x4ff
	v_cmp_lt_i32_e32 vcc, s6, v20
	s_and_saveexec_b64 s[42:43], vcc
	s_cbranch_execz .LBB0_815
	s_movk_i32 s6, 0x8ff
	v_cmp_lt_u32_e32 vcc, s6, v20
	s_nop 1
	v_cndmask_b32_e32 v21, 0, v198, vcc
	v_add_u32_e32 v21, v20, v21
	v_lshl_add_u32 v21, v21, 1, v199
	v_and_b32_e32 v21, 0xffffff00, v21
	v_cndmask_b32_e32 v22, 0, v200, vcc
	v_and_b32_e32 v20, 0x7f, v20
	v_or3_b32 v20, v21, v22, v20
	v_add_u32_e32 v20, 0x500, v20
.LBB0_815:
	s_or_b64 exec, exec, s[42:43]
	s_waitcnt lgkmcnt(3)
	v_pk_mul_f32 v[6:7], v[6:7], v[18:19]
	s_waitcnt lgkmcnt(2)
	v_pk_mul_f32 v[8:9], v[8:9], v[16:17]
	s_waitcnt lgkmcnt(1)
	v_pk_mul_f32 v[2:3], v[2:3], v[14:15]
	v_cvt_pk_bf16_f32 v6, v6, v7
	v_cvt_pk_bf16_f32 v7, v8, v9
	v_cvt_pk_bf16_f32 v8, v2, v3
	s_waitcnt lgkmcnt(0)
	v_pk_mul_f32 v[2:3], v[4:5], v[12:13]
	v_ashrrev_i32_e32 v21, 31, v20
	v_cvt_pk_bf16_f32 v9, v2, v3
	v_lshlrev_b64 v[2:3], 11, v[20:21]
	v_lshl_add_u64 v[2:3], v[10:11], 0, v[2:3]
	global_store_dwordx4 v[2:3], v[6:9], off sc1
	s_waitcnt lgkmcnt(0)
	s_branch .LBB0_793

; __device__ __forceinline__ void p0_pooleff_item(const float* wg, const float* scale, const float* wpb, bf16* WT, int item, int lane) {
;     ...
; #pragma unroll 1
;     for (int j0 = 0; j0 < 128; j0 += 16) {
;         float b[16];
; #pragma unroll
;         for (int u = 0; u < 16; ++u) b[u] = bp[(size_t)(j0 + u) * 1024];
; #pragma unroll
;         for (int u = 0; u < 16; ++u) { const float bb = b[u] * sp[j0 + u];
;             a0 += wgp[0 * 128 + j0 + u] * bb; a1 += wgp[1 * 128 + j0 + u] * bb; a2 += wgp[2 * 128 + j0 + u] * bb; a3 += wgp[3 * 128 + j0 + u] * bb;
;             a4 += wgp[4 * 128 + j0 + u] * bb; a5 += wgp[5 * 128 + j0 + u] * bb; a6 += wgp[6 * 128 + j0 + u] * bb; a7 += wgp[7 * 128 + j0 + u] * bb; }
.LBB0_817:
	v_add_co_u32_e32 v12, vcc, s83, v2
	global_load_dword v28, v[2:3], off
	s_nop 0
	v_addc_co_u32_e32 v13, vcc, 0, v3, vcc
	global_load_dword v29, v[12:13], off offset:-4096
	global_load_dword v30, v[12:13], off
	v_add_co_u32_e32 v12, vcc, s81, v2
	s_add_u32 s28, s23, s44
	s_nop 0
	v_addc_co_u32_e32 v13, vcc, 0, v3, vcc
	global_load_dword v31, v[12:13], off offset:-4096
	global_load_dword v32, v[12:13], off
	v_add_co_u32_e32 v12, vcc, s33, v2
	s_addc_u32 s29, s24, s45
	s_nop 0
	v_addc_co_u32_e32 v13, vcc, 0, v3, vcc
	global_load_dword v65, v[12:13], off offset:-4096
	global_load_dword v139, v[12:13], off
	v_add_co_u32_e32 v12, vcc, s79, v2
	s_nop 1
	v_addc_co_u32_e32 v13, vcc, 0, v3, vcc
	global_load_dword v141, v[12:13], off offset:-4096
	global_load_dword v143, v[12:13], off
	v_add_co_u32_e32 v12, vcc, s20, v2
	s_nop 1
	v_addc_co_u32_e32 v13, vcc, 0, v3, vcc
	global_load_dword v150, v[12:13], off offset:-4096
	global_load_dword v151, v[12:13], off
	v_add_co_u32_e32 v12, vcc, s0, v2
	s_nop 1
	v_addc_co_u32_e32 v13, vcc, 0, v3, vcc
	global_load_dword v152, v[12:13], off offset:-4096
	global_load_dword v153, v[12:13], off
	v_add_co_u32_e32 v12, vcc, s1, v2
	s_nop 1
	v_addc_co_u32_e32 v13, vcc, 0, v3, vcc
	global_load_dword v154, v[12:13], off offset:-4096
	global_load_dword v155, v[12:13], off
	v_add_co_u32_e32 v12, vcc, s21, v2
	s_nop 1
	v_addc_co_u32_e32 v13, vcc, 0, v3, vcc
	global_load_dword v156, v[12:13], off
	s_nop 0
	global_load_dwordx4 v[12:15], v66, s[28:29] offset:2096
	global_load_dwordx4 v[16:19], v66, s[28:29] offset:2080
	global_load_dwordx4 v[20:23], v66, s[28:29] offset:2064
	global_load_dwordx4 v[24:27], v66, s[28:29] offset:2048
	s_add_u32 s28, s25, s44
	s_addc_u32 s29, s26, s45
	s_add_u32 s30, s28, 0x40000
	s_addc_u32 s31, s29, 0
	s_add_u32 s34, s28, 0x40200
	s_addc_u32 s35, s29, 0
	s_add_u32 s36, s28, 0x40400
	s_addc_u32 s37, s29, 0
	s_add_u32 s48, s28, 0x40600
	s_addc_u32 s49, s29, 0
	s_add_u32 s50, s28, 0x40800
	s_addc_u32 s51, s29, 0
	s_add_u32 s56, s28, 0x40a00
	s_addc_u32 s57, s29, 0
	s_add_u32 s58, s28, 0x40c00
	s_addc_u32 s59, s29, 0
	s_add_u32 s60, s28, 0x40e00
	s_addc_u32 s61, s29, 0
	s_add_i32 s27, s27, 16
	s_add_u32 s44, s44, 64
	s_addc_u32 s45, s45, 0
	v_lshl_add_u64 v[2:3], v[2:3], 0, s[54:55]
	s_cmpk_lt_u32 s27, 0x70
	s_waitcnt vmcnt(0)
	v_mul_f32_e32 v12, v153, v12
	v_mul_f32_e32 v16, v143, v16
	v_mul_f32_e32 v20, v32, v20
	v_mul_f32_e32 v64, v28, v24
	v_mul_f32_e32 v138, v29, v25
	v_mul_f32_e32 v140, v30, v26
	v_mul_f32_e32 v142, v31, v27
	global_load_dwordx4 v[24:27], v66, s[30:31] offset:16
	global_load_dwordx4 v[28:31], v66, s[30:31] offset:48
	global_load_dwordx4 v[32:35], v66, s[30:31] offset:32
	global_load_dwordx4 v[36:39], v197, s[28:29]
	global_load_dwordx4 v[40:43], v66, s[34:35] offset:16
	global_load_dwordx4 v[44:47], v66, s[34:35] offset:48
	global_load_dwordx4 v[48:51], v66, s[34:35] offset:32
	global_load_dwordx4 v[52:55], v197, s[28:29] offset:512
	v_mul_f32_e32 v22, v139, v22
	v_mul_f32_e32 v18, v151, v18
	v_mul_f32_e32 v14, v155, v14
	s_waitcnt vmcnt(4)
	v_mov_b32_e32 v56, v36
	v_mov_b32_e32 v36, v38
	s_waitcnt vmcnt(0)
	v_mov_b32_e32 v57, v52
	v_pk_fma_f32 v[6:7], v[56:57], v[64:65], v[6:7] op_sel_hi:[1,0,1]
	v_mov_b32_e32 v52, v37
	v_pk_fma_f32 v[6:7], v[52:53], v[138:139], v[6:7] op_sel_hi:[1,0,1]
	v_mov_b32_e32 v37, v54
	v_pk_fma_f32 v[6:7], v[36:37], v[140:141], v[6:7] op_sel_hi:[1,0,1]
	v_mov_b32_e32 v54, v39
	v_pk_fma_f32 v[6:7], v[54:55], v[142:143], v[6:7] op_sel_hi:[1,0,1]
	v_mov_b32_e32 v36, v24
	v_mov_b32_e32 v37, v40
	v_pk_fma_f32 v[144:145], v[36:37], v[20:21], v[6:7] op_sel_hi:[1,0,1]
	global_load_dwordx4 v[36:39], v66, s[36:37] offset:16
	global_load_dwordx4 v[52:55], v66, s[36:37] offset:48
	global_load_dwordx4 v[56:59], v66, s[36:37] offset:32
	global_load_dwordx4 v[60:63], v197, s[28:29] offset:1024
	global_load_dwordx4 v[68:71], v66, s[48:49] offset:16
	global_load_dwordx4 v[72:75], v66, s[48:49] offset:48
	global_load_dwordx4 v[86:89], v66, s[48:49] offset:32
	global_load_dwordx4 v[90:93], v197, s[28:29] offset:1536
	v_mov_b32_e32 v40, v25
	v_mul_f32_e32 v24, v141, v23
	s_waitcnt vmcnt(4)
	v_mov_b32_e32 v6, v60
	s_waitcnt vmcnt(0)
	v_mov_b32_e32 v7, v90
	v_pk_fma_f32 v[6:7], v[64:65], v[6:7], v[8:9] op_sel_hi:[0,1,1]
	v_mov_b32_e32 v90, v61
	v_pk_fma_f32 v[6:7], v[138:139], v[90:91], v[6:7] op_sel_hi:[0,1,1]
	v_mov_b32_e32 v8, v62
	v_mov_b32_e32 v9, v92
	v_pk_fma_f32 v[6:7], v[140:141], v[8:9], v[6:7] op_sel_hi:[0,1,1]
	v_mov_b32_e32 v92, v63
	v_pk_fma_f32 v[6:7], v[142:143], v[92:93], v[6:7] op_sel_hi:[0,1,1]
	v_mov_b32_e32 v8, v36
	v_mov_b32_e32 v9, v68
	v_pk_fma_f32 v[146:147], v[20:21], v[8:9], v[6:7] op_sel_hi:[0,1,1]
	global_load_dwordx4 v[60:63], v66, s[50:51] offset:16
	global_load_dwordx4 v[90:93], v66, s[50:51] offset:48
	global_load_dwordx4 v[94:97], v66, s[50:51] offset:32
	global_load_dwordx4 v[6:9], v197, s[28:29] offset:2048
	global_load_dwordx4 v[98:101], v66, s[56:57] offset:16
	global_load_dwordx4 v[102:105], v66, s[56:57] offset:48
	global_load_dwordx4 v[106:109], v66, s[56:57] offset:32
	global_load_dwordx4 v[110:113], v197, s[28:29] offset:2560
	v_mul_f32_e32 v36, v150, v17
	v_mov_b32_e32 v68, v37
	s_waitcnt vmcnt(4)
	v_mov_b32_e32 v114, v6
	s_waitcnt vmcnt(0)
; __device__ __forceinline__ void p0_pooleff_item(const float* wg, const float* scale, const float* wpb, bf16* WT, int item, int lane) {
;     ...
; #pragma unroll 1
;     for (int j0 = 0; j0 < 128; j0 += 16) {
;         float b[16];
; #pragma unroll
;         for (int u = 0; u < 16; ++u) b[u] = bp[(size_t)(j0 + u) * 1024];
; #pragma unroll
;         for (int u = 0; u < 16; ++u) { const float bb = b[u] * sp[j0 + u];
;             a0 += wgp[0 * 128 + j0 + u] * bb; a1 += wgp[1 * 128 + j0 + u] * bb; a2 += wgp[2 * 128 + j0 + u] * bb; a3 += wgp[3 * 128 + j0 + u] * bb;
;             a4 += wgp[4 * 128 + j0 + u] * bb; a5 += wgp[5 * 128 + j0 + u] * bb; a6 += wgp[6 * 128 + j0 + u] * bb; a7 += wgp[7 * 128 + j0 + u] * bb; }
	v_mov_b32_e32 v115, v110
	v_pk_fma_f32 v[10:11], v[64:65], v[114:115], v[10:11] op_sel_hi:[0,1,1]
	v_mov_b32_e32 v110, v7
	v_pk_fma_f32 v[6:7], v[138:139], v[110:111], v[10:11] op_sel_hi:[0,1,1]
	v_mov_b32_e32 v10, v8
	v_mov_b32_e32 v11, v112
	v_pk_fma_f32 v[6:7], v[140:141], v[10:11], v[6:7] op_sel_hi:[0,1,1]
	v_mov_b32_e32 v112, v9
	v_pk_fma_f32 v[6:7], v[142:143], v[112:113], v[6:7] op_sel_hi:[0,1,1]
	v_mov_b32_e32 v8, v60
	v_mov_b32_e32 v9, v98
	v_pk_fma_f32 v[10:11], v[20:21], v[8:9], v[6:7] op_sel_hi:[0,1,1]
	global_load_dwordx4 v[110:113], v66, s[58:59] offset:16
	global_load_dwordx4 v[114:117], v66, s[58:59] offset:48
	global_load_dwordx4 v[118:121], v66, s[58:59] offset:32
	global_load_dwordx4 v[6:9], v197, s[28:29] offset:3072
	global_load_dwordx4 v[122:125], v66, s[60:61] offset:16
	global_load_dwordx4 v[126:129], v66, s[60:61] offset:48
	global_load_dwordx4 v[130:133], v66, s[60:61] offset:32
	global_load_dwordx4 v[134:137], v197, s[28:29] offset:3584
	v_mul_f32_e32 v60, v152, v19
	v_mov_b32_e32 v98, v61
	s_waitcnt vmcnt(4)
	v_mov_b32_e32 v148, v6
	v_mov_b32_e32 v6, v8
	v_mov_b32_e32 v8, v26
	v_mov_b32_e32 v26, v38
	s_waitcnt vmcnt(0)
	v_mov_b32_e32 v149, v134
	v_pk_fma_f32 v[4:5], v[64:65], v[148:149], v[4:5] op_sel_hi:[0,1,1]
	v_mov_b32_e32 v134, v7
	v_pk_fma_f32 v[4:5], v[138:139], v[134:135], v[4:5] op_sel_hi:[0,1,1]
	v_mov_b32_e32 v7, v136
	v_pk_fma_f32 v[4:5], v[140:141], v[6:7], v[4:5] op_sel_hi:[0,1,1]
	v_mov_b32_e32 v136, v9
	v_pk_fma_f32 v[4:5], v[142:143], v[136:137], v[4:5] op_sel_hi:[0,1,1]
	v_mov_b32_e32 v6, v110
	v_mov_b32_e32 v7, v122
	v_pk_fma_f32 v[4:5], v[20:21], v[6:7], v[4:5] op_sel_hi:[0,1,1]
	v_mul_f32_e32 v20, v65, v21
	v_pk_fma_f32 v[6:7], v[40:41], v[20:21], v[144:145] op_sel_hi:[1,0,1]
	v_mov_b32_e32 v9, v42
	v_pk_fma_f32 v[6:7], v[8:9], v[22:23], v[6:7] op_sel_hi:[1,0,1]
	v_mov_b32_e32 v42, v27
	v_pk_fma_f32 v[6:7], v[42:43], v[24:25], v[6:7] op_sel_hi:[1,0,1]
	v_mov_b32_e32 v8, v32
	v_mov_b32_e32 v9, v48
	v_pk_fma_f32 v[6:7], v[8:9], v[16:17], v[6:7] op_sel_hi:[1,0,1]
	v_mov_b32_e32 v48, v33
	v_pk_fma_f32 v[6:7], v[48:49], v[36:37], v[6:7] op_sel_hi:[1,0,1]
	v_mov_b32_e32 v8, v34
	v_mov_b32_e32 v9, v50
	v_pk_fma_f32 v[6:7], v[8:9], v[18:19], v[6:7] op_sel_hi:[1,0,1]
	v_mov_b32_e32 v50, v35
	v_pk_fma_f32 v[6:7], v[50:51], v[60:61], v[6:7] op_sel_hi:[1,0,1]
	v_mov_b32_e32 v8, v28
	v_mov_b32_e32 v9, v44
	v_mul_f32_e32 v64, v154, v13
	v_pk_fma_f32 v[6:7], v[8:9], v[12:13], v[6:7] op_sel_hi:[1,0,1]
	v_mov_b32_e32 v44, v29
	v_pk_fma_f32 v[6:7], v[44:45], v[64:65], v[6:7] op_sel_hi:[1,0,1]
	v_mov_b32_e32 v8, v30
	v_mov_b32_e32 v9, v46
	v_pk_fma_f32 v[6:7], v[8:9], v[14:15], v[6:7] op_sel_hi:[1,0,1]
	v_pk_fma_f32 v[8:9], v[20:21], v[68:69], v[146:147] op_sel_hi:[0,1,1]
	v_mov_b32_e32 v27, v70
	v_pk_fma_f32 v[8:9], v[22:23], v[26:27], v[8:9] op_sel_hi:[0,1,1]
	v_mov_b32_e32 v70, v39
	v_pk_fma_f32 v[8:9], v[24:25], v[70:71], v[8:9] op_sel_hi:[0,1,1]
	v_mov_b32_e32 v26, v56
	v_mov_b32_e32 v27, v86
	v_pk_fma_f32 v[8:9], v[16:17], v[26:27], v[8:9] op_sel_hi:[0,1,1]
	v_mov_b32_e32 v86, v57
	v_pk_fma_f32 v[8:9], v[36:37], v[86:87], v[8:9] op_sel_hi:[0,1,1]
	v_mov_b32_e32 v26, v58
	v_mov_b32_e32 v27, v88
	v_pk_fma_f32 v[8:9], v[18:19], v[26:27], v[8:9] op_sel_hi:[0,1,1]
	v_mov_b32_e32 v88, v59
	v_pk_fma_f32 v[8:9], v[60:61], v[88:89], v[8:9] op_sel_hi:[0,1,1]
	v_mov_b32_e32 v26, v52
	v_mov_b32_e32 v27, v72
	v_pk_fma_f32 v[8:9], v[12:13], v[26:27], v[8:9] op_sel_hi:[0,1,1]
	v_mov_b32_e32 v72, v53
	v_mov_b32_e32 v122, v111
	v_pk_fma_f32 v[8:9], v[64:65], v[72:73], v[8:9] op_sel_hi:[0,1,1]
	v_mov_b32_e32 v26, v54
	v_mov_b32_e32 v27, v74
	v_pk_fma_f32 v[8:9], v[14:15], v[26:27], v[8:9] op_sel_hi:[0,1,1]
	v_pk_fma_f32 v[10:11], v[20:21], v[98:99], v[10:11] op_sel_hi:[0,1,1]
	v_mov_b32_e32 v26, v62
	v_mov_b32_e32 v27, v100
	v_pk_fma_f32 v[4:5], v[20:21], v[122:123], v[4:5] op_sel_hi:[0,1,1]
	v_mov_b32_e32 v20, v112
	v_mov_b32_e32 v21, v124
	v_pk_fma_f32 v[10:11], v[22:23], v[26:27], v[10:11] op_sel_hi:[0,1,1]
	v_mov_b32_e32 v100, v63
	v_pk_fma_f32 v[4:5], v[22:23], v[20:21], v[4:5] op_sel_hi:[0,1,1]
	v_mov_b32_e32 v124, v113
	v_pk_fma_f32 v[10:11], v[24:25], v[100:101], v[10:11] op_sel_hi:[0,1,1]
	v_mov_b32_e32 v26, v94
	v_mov_b32_e32 v27, v106
	v_pk_fma_f32 v[4:5], v[24:25], v[124:125], v[4:5] op_sel_hi:[0,1,1]
	v_mov_b32_e32 v20, v118
	v_mov_b32_e32 v21, v130
	v_pk_fma_f32 v[10:11], v[16:17], v[26:27], v[10:11] op_sel_hi:[0,1,1]
	v_mov_b32_e32 v106, v95
	v_pk_fma_f32 v[4:5], v[16:17], v[20:21], v[4:5] op_sel_hi:[0,1,1]
	v_mov_b32_e32 v130, v119
	v_pk_fma_f32 v[10:11], v[36:37], v[106:107], v[10:11] op_sel_hi:[0,1,1]
	v_mov_b32_e32 v26, v96
	v_mov_b32_e32 v27, v108
	v_pk_fma_f32 v[4:5], v[36:37], v[130:131], v[4:5] op_sel_hi:[0,1,1]
	v_mov_b32_e32 v16, v120
	v_mov_b32_e32 v17, v132
	v_pk_fma_f32 v[10:11], v[18:19], v[26:27], v[10:11] op_sel_hi:[0,1,1]
	v_mov_b32_e32 v108, v97
	v_pk_fma_f32 v[4:5], v[18:19], v[16:17], v[4:5] op_sel_hi:[0,1,1]
	v_mov_b32_e32 v132, v121
	v_pk_fma_f32 v[10:11], v[60:61], v[108:109], v[10:11] op_sel_hi:[0,1,1]
	v_mov_b32_e32 v26, v90
	v_mov_b32_e32 v27, v102
	v_pk_fma_f32 v[4:5], v[60:61], v[132:133], v[4:5] op_sel_hi:[0,1,1]
	v_mov_b32_e32 v16, v114
	v_mov_b32_e32 v17, v126
	v_pk_fma_f32 v[10:11], v[12:13], v[26:27], v[10:11] op_sel_hi:[0,1,1]
	v_mov_b32_e32 v102, v91
	v_pk_fma_f32 v[4:5], v[12:13], v[16:17], v[4:5] op_sel_hi:[0,1,1]
	v_mov_b32_e32 v126, v115
	v_pk_fma_f32 v[10:11], v[64:65], v[102:103], v[10:11] op_sel_hi:[0,1,1]
	v_mov_b32_e32 v26, v92
	v_mov_b32_e32 v27, v104
	v_pk_fma_f32 v[4:5], v[64:65], v[126:127], v[4:5] op_sel_hi:[0,1,1]
	v_mov_b32_e32 v12, v116
	v_mov_b32_e32 v13, v128
	v_mul_f32_e32 v110, v156, v15
	v_mov_b32_e32 v46, v31
	v_mov_b32_e32 v74, v55
	v_pk_fma_f32 v[10:11], v[14:15], v[26:27], v[10:11] op_sel_hi:[0,1,1]
	v_mov_b32_e32 v104, v93
	v_pk_fma_f32 v[4:5], v[14:15], v[12:13], v[4:5] op_sel_hi:[0,1,1]
	v_mov_b32_e32 v128, v117
	v_pk_fma_f32 v[6:7], v[46:47], v[110:111], v[6:7] op_sel_hi:[1,0,1]
	v_pk_fma_f32 v[8:9], v[110:111], v[74:75], v[8:9] op_sel_hi:[0,1,1]
	v_pk_fma_f32 v[10:11], v[110:111], v[104:105], v[10:11] op_sel_hi:[0,1,1]
	v_pk_fma_f32 v[4:5], v[110:111], v[128:129], v[4:5] op_sel_hi:[0,1,1]
	s_cbranch_scc1 .LBB0_817
; #define GAS __attribute__((address_space(1)))
; __device__ __forceinline__ unsigned pk2(float lo, float hi) { f32x2p v = {lo, hi}; bf16x2p b = __builtin_convertvector(v, bf16x2p); return __builtin_bit_cast(unsigned, b); }
; __device__ __forceinline__ void p0_pooleff_item(const float* wg, const float* scale, const float* wpb, bf16* WT, int item, int lane) {
;     ...
;     v4u o; o.x = pk2(a0, a1); o.y = pk2(a2, a3); o.z = pk2(a4, a5); o.w = pk2(a6, a7);
;     *(GAS v4u*)(WT + (size_t)n * 1024 + g * 128 + cblk * 8) = o;
	s_lshl_b32 s23, s47, 6
	s_and_b32 s23, s23, 0x3c0
	v_add_u32_e32 v2, s23, v67
	v_ashrrev_i32_e32 v3, 31, v2
	v_readlane_b32 s4, v241, 19
	v_lshlrev_b64 v[2:3], 11, v[2:3]
	v_readlane_b32 s5, v241, 20
	s_and_b32 s84, s47, 0xf0
	v_cvt_pk_bf16_f32 v6, v6, v7
	v_lshl_add_u64 v[2:3], s[4:5], 0, v[2:3]
	v_lshl_add_u64 v[2:3], s[42:43], 1, v[2:3]
	v_cvt_pk_bf16_f32 v7, v8, v9
	v_cvt_pk_bf16_f32 v8, v10, v11
	v_cvt_pk_bf16_f32 v9, v4, v5
	v_lshl_add_u64 v[2:3], v[2:3], 0, s[84:85]
	v_readlane_b32 s4, v242, 0
	v_readlane_b32 s8, v238, 33
	v_readlane_b32 s10, v238, 35
	v_readlane_b32 s14, v238, 37
	v_readlane_b32 s16, v242, 62
	v_readlane_b32 s18, v240, 0
	v_readlane_b32 s34, v240, 2
	global_store_dwordx4 v[2:3], v[6:9], off sc1
	v_readlane_b32 s2, v242, 4
	v_readlane_b32 s5, v242, 1
	v_readlane_b32 s9, v238, 34
	v_readlane_b32 s11, v238, 36
	v_readlane_b32 s15, v238, 38
	v_readlane_b32 s17, v242, 63
	v_readlane_b32 s19, v240, 1
	v_readlane_b32 s35, v240, 3
	s_branch .LBB0_793

; __device__ __forceinline__ unsigned xb_ld(unsigned* p)              { return __hip_atomic_load(p, __ATOMIC_RELAXED, __HIP_MEMORY_SCOPE_AGENT); }
; __device__ __forceinline__ unsigned xb_add(unsigned* p, unsigned v) { return __hip_atomic_fetch_add(p, v, __ATOMIC_RELAXED, __HIP_MEMORY_SCOPE_AGENT); }
; #define XB_SPIN(cond, bar) do { unsigned _sp = 0; while (cond) { __builtin_amdgcn_s_sleep(1); \
;     if ((++_sp & 255u) == 0u) { if (xb_ld(&(bar)[XB_TMO])) break; if (_sp > XB_SPIN_CAP) { atomicAdd(&(bar)[XB_TMO], 1u); break; } } } } while (0)
; #define SEAM_G(k) do { if (IN(k) && IN((k) + 1)) { if (xl_fast) xcc_local_barrier(ctl + CW_BAR2, bar.x, bar.st[0], bar.bar); else xcd_barrier(bar); } } while (0)
; #define SEAM_G(k) SEAM(k)
; __device__ __forceinline__ void xcc_local_barrier(unsigned* bar2, unsigned x, unsigned nloc, unsigned* tmobar) {
;     asm volatile("s_waitcnt vmcnt(0)" ::: "memory");
;     __syncthreads();
;     if (threadIdx.x == 0) {
;         const unsigned old = xb_add(&bar2[XB_XSUB(x)], 1u);
;         const unsigned gen = old / nloc;
;         if (old + 1u == (gen + 1u) * nloc) (void)xb_add(&bar2[XB_XGEN(x)], 1u);
;         else XB_SPIN(xb_ld(&bar2[XB_XGEN(x)]) == gen, tmobar);
;         __builtin_amdgcn_fence(__ATOMIC_ACQUIRE, "agent");
;         asm volatile("s_waitcnt vmcnt(0)" ::: "memory");
;     }
;     __syncthreads();
; }
; __global__ void __launch_bounds__(NWAVES * 64, 2) mk_fwd(Args args) {
;     ...
;         SEAM_G(pb + 4);
.LBB0_874:
	s_and_b64 vcc, exec, s[38:39]
	s_cbranch_vccz .LBB0_894
	v_readlane_b32 s6, v238, 25
	s_nop 1
	v_mov_b32_e32 v2, s6
	ds_read_b32 v2, v2
	s_waitcnt vmcnt(0)
	v_readlane_b32 s6, v242, 38
	v_readlane_b32 s7, v242, 39
	s_waitcnt vmcnt(0) lgkmcnt(0)
	s_barrier
	s_and_saveexec_b64 s[38:39], s[6:7]
	s_cbranch_execz .LBB0_893
	v_readlane_b32 s6, v240, 60
	v_readlane_b32 s7, v240, 61
	v_mov_b32_e32 v3, 1
	s_nop 4
	global_atomic_add v66, v3, s[6:7] offset:576
	s_add_i32 s101, s101, 1
	v_readlane_b32 s6, v239, 63
	v_readlane_b32 s7, v241, 0
	v_readlane_b32 s98, v242, 4
	v_mov_b32_e32 v3, s101
	s_nop 3
	s_lshr_b32 s98, s98, 6
	s_lshl_b32 s98, s98, 2
	v_mov_b32_e32 v4, s98
	global_store_dword v4, v3, s[6:7] offset:128 sc1
	buffer_inv sc1
	s_mov_b32 s100, 0

; #define SEAM(k) do { if (IN(k) && IN((k) + 1)) { xcd_barrier(bar); xcd_barrier(bar); } } while (0)
; #define SEAM(k) do { if (IN(k) && IN((k) + 1)) xcd_barrier(bar); } while (0)
; #define SEAM_G(k) do { if (IN(k) && IN((k) + 1)) { if (xl_fast) xcc_local_barrier(ctl + CW_BAR2, bar.x, bar.st[0], bar.bar); else xcd_barrier(bar); } } while (0)
; #define SEAM_G(k) SEAM(k)
; __device__ __forceinline__ void xcd_barrier(const XcdBarrier& b) {
;     asm volatile("s_waitcnt vmcnt(0)" ::: "memory");
;     __syncthreads();
;     if (threadIdx.x == 0) {
; __global__ void __launch_bounds__(NWAVES * 64, 2) mk_fwd(Args args) {
;     ...
;         if (l == DEPTH - 1) SEAM_G(pb + 5); else SEAM(pb + 5);
.LBB0_932:
	v_readlane_b32 s6, v238, 44
	s_add_i32 s23, s6, 7
	s_cmp_lt_i32 s23, s5
	v_readlane_b32 s6, v238, 51
	s_cselect_b64 s[24:25], -1, 0
	v_readlane_b32 s7, v238, 52
	s_and_b64 s[36:37], s[42:43], s[24:25]
	s_and_b64 vcc, exec, s[6:7]
	s_cbranch_vccz .LBB0_945
	v_readlane_b32 s28, v240, 2
	s_mov_b64 s[38:39], 0
	s_and_b64 vcc, exec, s[36:37]
	s_mov_b64 s[40:41], 0
	v_readlane_b32 s29, v240, 3
	s_cbranch_vccz .LBB0_946
	s_waitcnt vmcnt(0)
	v_readlane_b32 s6, v242, 38
	v_readlane_b32 s7, v242, 39
	s_waitcnt vmcnt(0) lgkmcnt(0)
	s_barrier
	s_and_saveexec_b64 s[40:41], s[6:7]
	s_cbranch_execz .LBB0_1018
	v_readlane_b32 s6, v242, 52
	v_readlane_b32 s7, v242, 53
	s_nop 3
	s_cmp_eq_u64 s[6:7], 0
	s_cbranch_scc0 .Lpf_seam_grid
	v_readlane_b32 s6, v240, 60
	v_readlane_b32 s7, v240, 61
	s_mov_b32 s99, 0
	s_nop 4
.Lcw_poll:
	global_load_dword v3, v66, s[6:7] offset:576 sc1
	s_waitcnt vmcnt(0)
	v_cmp_le_u32_e32 vcc, 0x100, v3
	s_cbranch_vccnz .Lcw_done
	s_sleep 1
	s_add_i32 s99, s99, 1
	s_cmp_lt_u32 s99, 0x10000
	s_cbranch_scc1 .Lcw_poll

; #define SEAM(k) do { if (IN(k) && IN((k) + 1)) { xcd_barrier(bar); xcd_barrier(bar); } } while (0)
; #define SEAM(k) do { if (IN(k) && IN((k) + 1)) xcd_barrier(bar); } while (0)
; #define SEAM_G(k) do { if (IN(k) && IN((k) + 1)) { if (xl_fast) xcc_local_barrier(ctl + CW_BAR2, bar.x, bar.st[0], bar.bar); else xcd_barrier(bar); } } while (0)
; #define SEAM_G(k) SEAM(k)
; __device__ __forceinline__ void xcd_barrier(const XcdBarrier& b) {
;     asm volatile("s_waitcnt vmcnt(0)" ::: "memory");
;     __syncthreads();
;     if (threadIdx.x == 0) {
;         unsigned* bar = b.bar;
;         __builtin_amdgcn_s_waitcnt(0);
;         unsigned nloc = b.st[0], nx = b.st[1];
;         if (nloc == 0u) { xcd_barrier_complete(bar, b.x, nloc, nx); b.st[0] = nloc; b.st[1] = nx; }
; __global__ void __launch_bounds__(NWAVES * 64, 2) mk_fwd(Args args) {
;     ...
;         if (l == DEPTH - 1) SEAM_G(pb + 5); else SEAM(pb + 5);
.Lgrp_poll_5:
	global_load_dwordx4 v[4:7], v66, s[6:7] offset:128 sc1
	s_waitcnt vmcnt(0)
	v_min_u32_e32 v4, v4, v5
	v_min3_u32 v4, v4, v6, v7
	s_nop 0
	v_readfirstlane_b32 s98, v4
	s_nop 3
	s_cmp_ge_u32 s98, s101
	s_cbranch_scc1 .Lgrp_done_5
	s_sleep 1
	s_add_i32 s100, s100, 1
	s_cmp_lt_u32 s100, 0x10000
	s_cbranch_scc1 .Lgrp_poll_5
.Lgrp_done_5:
	s_waitcnt vmcnt(0)
	s_branch .LBB0_1018
.Lpf_seam_grid:
	v_readlane_b32 s6, v238, 25
	s_waitcnt vmcnt(0) expcnt(0) lgkmcnt(0)
	s_nop 0
	v_mov_b32_e32 v2, s6
	ds_read_b32 v4, v2
	v_readlane_b32 s6, v238, 26
	s_waitcnt lgkmcnt(0)
	v_cmp_ne_u32_e32 vcc, 0, v4
	v_mov_b32_e32 v2, s6
	ds_read_b32 v2, v2
	s_cbranch_vccnz .LBB0_965
	v_readlane_b32 s12, v242, 2
	v_readlane_b32 s13, v242, 3
	s_load_dwordx2 s[24:25], s[12:13], 0x4
	s_waitcnt lgkmcnt(0)
	s_mul_i32 s23, s24, s96
	s_mul_i32 s23, s23, s25
	s_mov_b32 s24, 1
	s_branch .LBB0_938
